# v7 + per-unit accumulator zeroing with 64 v_mov_b64 instead of 128 v_mov_b32 in all 12 GEMM phases
# speedup vs baseline: 1.0033x; 1.0033x over previous
.LBB0_37:
	s_add_u32 s21, s10, 0x100
	v_mov_b64_e32 v[0:1], 0
	s_addc_u32 s90, s11, 0
	s_mov_b32 s22, -2
	v_mov_b64_e32 v[2:3], 0
	v_mov_b64_e32 v[4:5], 0
	v_mov_b64_e32 v[6:7], 0
	v_mov_b64_e32 v[16:17], 0
	v_mov_b64_e32 v[18:19], 0
	v_mov_b64_e32 v[20:21], 0
	v_mov_b64_e32 v[22:23], 0
	v_mov_b64_e32 v[32:33], 0
	v_mov_b64_e32 v[34:35], 0
	v_mov_b64_e32 v[36:37], 0
	v_mov_b64_e32 v[38:39], 0
	v_mov_b64_e32 v[48:49], 0
	v_mov_b64_e32 v[50:51], 0
	v_mov_b64_e32 v[52:53], 0
	v_mov_b64_e32 v[54:55], 0
	v_mov_b64_e32 v[8:9], 0
	v_mov_b64_e32 v[10:11], 0
	v_mov_b64_e32 v[12:13], 0
	v_mov_b64_e32 v[14:15], 0
	v_mov_b64_e32 v[24:25], 0
	v_mov_b64_e32 v[26:27], 0
	v_mov_b64_e32 v[28:29], 0
	v_mov_b64_e32 v[30:31], 0
	v_mov_b64_e32 v[40:41], 0
	v_mov_b64_e32 v[42:43], 0
	v_mov_b64_e32 v[44:45], 0
	v_mov_b64_e32 v[46:47], 0
	v_mov_b64_e32 v[56:57], 0
	v_mov_b64_e32 v[58:59], 0
	v_mov_b64_e32 v[60:61], 0
	v_mov_b64_e32 v[62:63], 0
	v_mov_b64_e32 v[64:65], 0
	v_mov_b64_e32 v[66:67], 0
	v_mov_b64_e32 v[68:69], 0
	v_mov_b64_e32 v[70:71], 0
	v_mov_b64_e32 v[80:81], 0
	v_mov_b64_e32 v[82:83], 0
	v_mov_b64_e32 v[84:85], 0
	v_mov_b64_e32 v[86:87], 0
	v_mov_b64_e32 v[96:97], 0
	v_mov_b64_e32 v[98:99], 0
	v_mov_b64_e32 v[100:101], 0
	v_mov_b64_e32 v[102:103], 0
	v_mov_b64_e32 v[112:113], 0
	v_mov_b64_e32 v[114:115], 0
	v_mov_b64_e32 v[116:117], 0
	v_mov_b64_e32 v[118:119], 0
	v_mov_b64_e32 v[72:73], 0
	v_mov_b64_e32 v[74:75], 0
	v_mov_b64_e32 v[76:77], 0
	v_mov_b64_e32 v[78:79], 0
	v_mov_b64_e32 v[88:89], 0
	v_mov_b64_e32 v[90:91], 0
	v_mov_b64_e32 v[92:93], 0
	v_mov_b64_e32 v[94:95], 0
	v_mov_b64_e32 v[104:105], 0
	v_mov_b64_e32 v[106:107], 0
	v_mov_b64_e32 v[108:109], 0
	v_mov_b64_e32 v[110:111], 0
	v_mov_b64_e32 v[120:121], 0
	v_mov_b64_e32 v[122:123], 0
	v_mov_b64_e32 v[124:125], 0
	v_mov_b64_e32 v[126:127], 0

.LBB0_55:
	s_ashr_i32 s37, s36, 31
	s_lshl_b64 s[14:15], s[36:37], 19
	s_add_u32 s44, s24, s14
	s_addc_u32 s45, s25, s15
	s_and_b64 s[14:15], s[38:39], exec
	s_cselect_b32 s20, s45, s13
	s_cselect_b32 s37, s44, s12
	s_ashr_i32 s41, s40, 31
	s_lshl_b64 s[14:15], s[40:41], 19
	s_add_u32 s92, s26, s14
	s_addc_u32 s93, s27, s15
	s_and_b64 s[14:15], s[38:39], exec
	s_cselect_b32 s41, s93, s11
	s_cselect_b32 s91, s92, s10
	s_add_u32 s96, s10, 0x100
	s_addc_u32 s21, s11, 0
	s_add_u32 s10, s12, 0x40080
	v_mov_b64_e32 v[4:5], 0
	s_addc_u32 s11, s13, 0
	s_mov_b32 s22, -2
	v_mov_b64_e32 v[6:7], 0
	v_mov_b64_e32 v[8:9], 0
	v_mov_b64_e32 v[10:11], 0
	v_mov_b64_e32 v[20:21], 0
	v_mov_b64_e32 v[22:23], 0
	v_mov_b64_e32 v[24:25], 0
	v_mov_b64_e32 v[26:27], 0
	v_mov_b64_e32 v[36:37], 0
	v_mov_b64_e32 v[38:39], 0
	v_mov_b64_e32 v[40:41], 0
	v_mov_b64_e32 v[42:43], 0
	v_mov_b64_e32 v[52:53], 0
	v_mov_b64_e32 v[54:55], 0
	v_mov_b64_e32 v[56:57], 0
	v_mov_b64_e32 v[58:59], 0
	v_mov_b64_e32 v[0:1], 0
	v_mov_b64_e32 v[2:3], 0
	v_mov_b64_e32 v[12:13], 0
	v_mov_b64_e32 v[14:15], 0
	v_mov_b64_e32 v[16:17], 0
	v_mov_b64_e32 v[18:19], 0
	v_mov_b64_e32 v[28:29], 0
	v_mov_b64_e32 v[30:31], 0
	v_mov_b64_e32 v[32:33], 0
	v_mov_b64_e32 v[34:35], 0
	v_mov_b64_e32 v[44:45], 0
	v_mov_b64_e32 v[46:47], 0
	v_mov_b64_e32 v[48:49], 0
	v_mov_b64_e32 v[50:51], 0
	v_mov_b64_e32 v[60:61], 0
	v_mov_b64_e32 v[62:63], 0
	v_mov_b64_e32 v[68:69], 0
	v_mov_b64_e32 v[70:71], 0
	v_mov_b64_e32 v[72:73], 0
	v_mov_b64_e32 v[74:75], 0
	v_mov_b64_e32 v[80:81], 0
	v_mov_b64_e32 v[82:83], 0
	v_mov_b64_e32 v[88:89], 0
	v_mov_b64_e32 v[90:91], 0
	v_mov_b64_e32 v[96:97], 0
	v_mov_b64_e32 v[98:99], 0
	v_mov_b64_e32 v[104:105], 0
	v_mov_b64_e32 v[106:107], 0
	v_mov_b64_e32 v[112:113], 0
	v_mov_b64_e32 v[114:115], 0
	v_mov_b64_e32 v[120:121], 0
	v_mov_b64_e32 v[122:123], 0
	v_mov_b64_e32 v[64:65], 0
	v_mov_b64_e32 v[66:67], 0
	v_mov_b64_e32 v[76:77], 0
	v_mov_b64_e32 v[78:79], 0
	v_mov_b64_e32 v[84:85], 0
	v_mov_b64_e32 v[86:87], 0
	v_mov_b64_e32 v[92:93], 0
	v_mov_b64_e32 v[94:95], 0
	v_mov_b64_e32 v[100:101], 0
	v_mov_b64_e32 v[102:103], 0
	v_mov_b64_e32 v[108:109], 0
	v_mov_b64_e32 v[110:111], 0
	v_mov_b64_e32 v[116:117], 0
	v_mov_b64_e32 v[118:119], 0
	v_mov_b64_e32 v[124:125], 0
	v_mov_b64_e32 v[126:127], 0

.LBB0_83:
	s_ashr_i32 s37, s36, 31
	s_lshl_b64 s[20:21], s[36:37], 19
	s_add_u32 s92, s24, s20
	s_addc_u32 s93, s25, s21
	s_and_b64 s[20:21], s[40:41], exec
	s_cselect_b32 s9, s93, s15
	s_cselect_b32 s20, s92, s14
	s_ashr_i32 s45, s44, 31
	s_lshl_b64 s[48:49], s[44:45], 19
	s_add_u32 s96, s26, s48
	s_addc_u32 s97, s27, s49
	s_and_b64 s[48:49], s[40:41], exec
	s_cselect_b32 s37, s97, s13
	s_cselect_b32 s45, s96, s12
	s_add_u32 s90, s12, 0x100
	s_addc_u32 s21, s13, 0
	s_add_u32 vcc_lo, s14, 0x40080
	v_mov_b64_e32 v[0:1], 0
	s_addc_u32 vcc_hi, s15, 0
	s_mov_b32 s22, -2
	v_mov_b64_e32 v[2:3], 0
	v_mov_b64_e32 v[4:5], 0
	v_mov_b64_e32 v[6:7], 0
	v_mov_b64_e32 v[16:17], 0
	v_mov_b64_e32 v[18:19], 0
	v_mov_b64_e32 v[20:21], 0
	v_mov_b64_e32 v[22:23], 0
	v_mov_b64_e32 v[32:33], 0
	v_mov_b64_e32 v[34:35], 0
	v_mov_b64_e32 v[36:37], 0
	v_mov_b64_e32 v[38:39], 0
	v_mov_b64_e32 v[48:49], 0
	v_mov_b64_e32 v[50:51], 0
	v_mov_b64_e32 v[52:53], 0
	v_mov_b64_e32 v[54:55], 0
	v_mov_b64_e32 v[8:9], 0
	v_mov_b64_e32 v[10:11], 0
	v_mov_b64_e32 v[12:13], 0
	v_mov_b64_e32 v[14:15], 0
	v_mov_b64_e32 v[24:25], 0
	v_mov_b64_e32 v[26:27], 0
	v_mov_b64_e32 v[28:29], 0
	v_mov_b64_e32 v[30:31], 0
	v_mov_b64_e32 v[40:41], 0
	v_mov_b64_e32 v[42:43], 0
	v_mov_b64_e32 v[44:45], 0
	v_mov_b64_e32 v[46:47], 0
	v_mov_b64_e32 v[56:57], 0
	v_mov_b64_e32 v[58:59], 0
	v_mov_b64_e32 v[60:61], 0
	v_mov_b64_e32 v[62:63], 0
	v_mov_b64_e32 v[64:65], 0
	v_mov_b64_e32 v[66:67], 0
	v_mov_b64_e32 v[68:69], 0
	v_mov_b64_e32 v[70:71], 0
	v_mov_b64_e32 v[80:81], 0
	v_mov_b64_e32 v[82:83], 0
	v_mov_b64_e32 v[84:85], 0
	v_mov_b64_e32 v[86:87], 0
	v_mov_b64_e32 v[96:97], 0
	v_mov_b64_e32 v[98:99], 0
	v_mov_b64_e32 v[100:101], 0
	v_mov_b64_e32 v[102:103], 0
	v_mov_b64_e32 v[112:113], 0
	v_mov_b64_e32 v[114:115], 0
	v_mov_b64_e32 v[116:117], 0
	v_mov_b64_e32 v[118:119], 0
	v_mov_b64_e32 v[72:73], 0
	v_mov_b64_e32 v[74:75], 0
	v_mov_b64_e32 v[76:77], 0
	v_mov_b64_e32 v[78:79], 0
	v_mov_b64_e32 v[88:89], 0
	v_mov_b64_e32 v[90:91], 0
	v_mov_b64_e32 v[92:93], 0
	v_mov_b64_e32 v[94:95], 0
	v_mov_b64_e32 v[104:105], 0
	v_mov_b64_e32 v[106:107], 0
	v_mov_b64_e32 v[108:109], 0
	v_mov_b64_e32 v[110:111], 0
	v_mov_b64_e32 v[120:121], 0
	v_mov_b64_e32 v[122:123], 0
	v_mov_b64_e32 v[124:125], 0
	v_mov_b64_e32 v[126:127], 0

.LBB0_138:
	s_ashr_i32 s41, s40, 31
	s_lshl_b64 s[12:13], s[40:41], 19
	s_add_u32 s12, s25, s12
	s_addc_u32 s13, s26, s13
	s_and_b64 s[14:15], s[38:39], exec
	s_cselect_b32 s9, s13, s93
	s_cselect_b32 s41, s12, s92
	s_ashr_i32 s45, s44, 31
	s_lshl_b64 s[14:15], s[44:45], 19
	s_add_u32 s96, s27, s14
	s_addc_u32 s97, s28, s15
	s_and_b64 s[14:15], s[38:39], exec
	s_cselect_b32 s45, s97, s11
	s_cselect_b32 vcc_lo, s96, s10
	s_add_u32 vcc_hi, s10, 0x100
	s_addc_u32 s21, s11, 0
	s_add_u32 s10, s92, 0x40080
	v_mov_b64_e32 v[0:1], 0
	s_addc_u32 s11, s93, 0
	s_mov_b32 s22, -2
	v_mov_b64_e32 v[2:3], 0
	v_mov_b64_e32 v[4:5], 0
	v_mov_b64_e32 v[6:7], 0
	v_mov_b64_e32 v[16:17], 0
	v_mov_b64_e32 v[18:19], 0
	v_mov_b64_e32 v[20:21], 0
	v_mov_b64_e32 v[22:23], 0
	v_mov_b64_e32 v[32:33], 0
	v_mov_b64_e32 v[34:35], 0
	v_mov_b64_e32 v[36:37], 0
	v_mov_b64_e32 v[38:39], 0
	v_mov_b64_e32 v[48:49], 0
	v_mov_b64_e32 v[50:51], 0
	v_mov_b64_e32 v[52:53], 0
	v_mov_b64_e32 v[54:55], 0
	v_mov_b64_e32 v[8:9], 0
	v_mov_b64_e32 v[10:11], 0
	v_mov_b64_e32 v[12:13], 0
	v_mov_b64_e32 v[14:15], 0
	v_mov_b64_e32 v[24:25], 0
	v_mov_b64_e32 v[26:27], 0
	v_mov_b64_e32 v[28:29], 0
	v_mov_b64_e32 v[30:31], 0
	v_mov_b64_e32 v[40:41], 0
	v_mov_b64_e32 v[42:43], 0
	v_mov_b64_e32 v[44:45], 0
	v_mov_b64_e32 v[46:47], 0
	v_mov_b64_e32 v[56:57], 0
	v_mov_b64_e32 v[58:59], 0
	v_mov_b64_e32 v[60:61], 0
	v_mov_b64_e32 v[62:63], 0
	v_mov_b64_e32 v[64:65], 0
	v_mov_b64_e32 v[66:67], 0
	v_mov_b64_e32 v[68:69], 0
	v_mov_b64_e32 v[70:71], 0
	v_mov_b64_e32 v[80:81], 0
	v_mov_b64_e32 v[82:83], 0
	v_mov_b64_e32 v[84:85], 0
	v_mov_b64_e32 v[86:87], 0
	v_mov_b64_e32 v[96:97], 0
	v_mov_b64_e32 v[98:99], 0
	v_mov_b64_e32 v[100:101], 0
	v_mov_b64_e32 v[102:103], 0
	v_mov_b64_e32 v[112:113], 0
	v_mov_b64_e32 v[114:115], 0
	v_mov_b64_e32 v[116:117], 0
	v_mov_b64_e32 v[118:119], 0
	v_mov_b64_e32 v[72:73], 0
	v_mov_b64_e32 v[74:75], 0
	v_mov_b64_e32 v[76:77], 0
	v_mov_b64_e32 v[78:79], 0
	v_mov_b64_e32 v[88:89], 0
	v_mov_b64_e32 v[90:91], 0
	v_mov_b64_e32 v[92:93], 0
	v_mov_b64_e32 v[94:95], 0
	v_mov_b64_e32 v[104:105], 0
	v_mov_b64_e32 v[106:107], 0
	v_mov_b64_e32 v[108:109], 0
	v_mov_b64_e32 v[110:111], 0
	v_mov_b64_e32 v[120:121], 0
	v_mov_b64_e32 v[122:123], 0
	v_mov_b64_e32 v[124:125], 0
	v_mov_b64_e32 v[126:127], 0

.LBB0_177:
	s_add_u32 s21, s10, 0x100
	v_mov_b64_e32 v[0:1], 0
	s_addc_u32 s96, s11, 0
	s_mov_b32 s22, -2
	v_mov_b64_e32 v[2:3], 0
	v_mov_b64_e32 v[4:5], 0
	v_mov_b64_e32 v[6:7], 0
	v_mov_b64_e32 v[16:17], 0
	v_mov_b64_e32 v[18:19], 0
	v_mov_b64_e32 v[20:21], 0
	v_mov_b64_e32 v[22:23], 0
	v_mov_b64_e32 v[32:33], 0
	v_mov_b64_e32 v[34:35], 0
	v_mov_b64_e32 v[36:37], 0
	v_mov_b64_e32 v[38:39], 0
	v_mov_b64_e32 v[48:49], 0
	v_mov_b64_e32 v[50:51], 0
	v_mov_b64_e32 v[52:53], 0
	v_mov_b64_e32 v[54:55], 0
	v_mov_b64_e32 v[8:9], 0
	v_mov_b64_e32 v[10:11], 0
	v_mov_b64_e32 v[12:13], 0
	v_mov_b64_e32 v[14:15], 0
	v_mov_b64_e32 v[24:25], 0
	v_mov_b64_e32 v[26:27], 0
	v_mov_b64_e32 v[28:29], 0
	v_mov_b64_e32 v[30:31], 0
	v_mov_b64_e32 v[40:41], 0
	v_mov_b64_e32 v[42:43], 0
	v_mov_b64_e32 v[44:45], 0
	v_mov_b64_e32 v[46:47], 0
	v_mov_b64_e32 v[56:57], 0
	v_mov_b64_e32 v[58:59], 0
	v_mov_b64_e32 v[60:61], 0
	v_mov_b64_e32 v[62:63], 0
	v_mov_b64_e32 v[64:65], 0
	v_mov_b64_e32 v[66:67], 0
	v_mov_b64_e32 v[68:69], 0
	v_mov_b64_e32 v[70:71], 0
	v_mov_b64_e32 v[80:81], 0
	v_mov_b64_e32 v[82:83], 0
	v_mov_b64_e32 v[84:85], 0
	v_mov_b64_e32 v[86:87], 0
	v_mov_b64_e32 v[96:97], 0
	v_mov_b64_e32 v[98:99], 0
	v_mov_b64_e32 v[100:101], 0
	v_mov_b64_e32 v[102:103], 0
	v_mov_b64_e32 v[112:113], 0
	v_mov_b64_e32 v[114:115], 0
	v_mov_b64_e32 v[116:117], 0
	v_mov_b64_e32 v[118:119], 0
	v_mov_b64_e32 v[72:73], 0
	v_mov_b64_e32 v[74:75], 0
	v_mov_b64_e32 v[76:77], 0
	v_mov_b64_e32 v[78:79], 0
	v_mov_b64_e32 v[88:89], 0
	v_mov_b64_e32 v[90:91], 0
	v_mov_b64_e32 v[92:93], 0
	v_mov_b64_e32 v[94:95], 0
	v_mov_b64_e32 v[104:105], 0
	v_mov_b64_e32 v[106:107], 0
	v_mov_b64_e32 v[108:109], 0
	v_mov_b64_e32 v[110:111], 0
	v_mov_b64_e32 v[120:121], 0
	v_mov_b64_e32 v[122:123], 0
	v_mov_b64_e32 v[124:125], 0
	v_mov_b64_e32 v[126:127], 0

.LBB0_211:
	s_ashr_i32 s37, s36, 31
	s_lshl_b64 s[14:15], s[36:37], 19
	s_add_u32 s44, s24, s14
	s_addc_u32 s45, s25, s15
	s_and_b64 s[14:15], s[38:39], exec
	s_cselect_b32 s20, s45, s13
	s_cselect_b32 s37, s44, s12
	s_ashr_i32 s41, s40, 31
	s_lshl_b64 s[14:15], s[40:41], 19
	s_add_u32 s92, s26, s14
	s_addc_u32 s93, s27, s15
	s_and_b64 s[14:15], s[38:39], exec
	s_cselect_b32 s41, s93, s11
	s_cselect_b32 s91, s92, s10
	s_add_u32 s96, s10, 0x100
	s_addc_u32 s97, s11, 0
	s_add_u32 s10, s12, 0x40080
	v_mov_b64_e32 v[4:5], 0
	s_addc_u32 s11, s13, 0
	s_mov_b32 s21, -2
	v_mov_b64_e32 v[6:7], 0
	v_mov_b64_e32 v[8:9], 0
	v_mov_b64_e32 v[10:11], 0
	v_mov_b64_e32 v[20:21], 0
	v_mov_b64_e32 v[22:23], 0
	v_mov_b64_e32 v[24:25], 0
	v_mov_b64_e32 v[26:27], 0
	v_mov_b64_e32 v[36:37], 0
	v_mov_b64_e32 v[38:39], 0
	v_mov_b64_e32 v[40:41], 0
	v_mov_b64_e32 v[42:43], 0
	v_mov_b64_e32 v[52:53], 0
	v_mov_b64_e32 v[54:55], 0
	v_mov_b64_e32 v[56:57], 0
	v_mov_b64_e32 v[58:59], 0
	v_mov_b64_e32 v[0:1], 0
	v_mov_b64_e32 v[2:3], 0
	v_mov_b64_e32 v[12:13], 0
	v_mov_b64_e32 v[14:15], 0
	v_mov_b64_e32 v[16:17], 0
	v_mov_b64_e32 v[18:19], 0
	v_mov_b64_e32 v[28:29], 0
	v_mov_b64_e32 v[30:31], 0
	v_mov_b64_e32 v[32:33], 0
	v_mov_b64_e32 v[34:35], 0
	v_mov_b64_e32 v[44:45], 0
	v_mov_b64_e32 v[46:47], 0
	v_mov_b64_e32 v[48:49], 0
	v_mov_b64_e32 v[50:51], 0
	v_mov_b64_e32 v[60:61], 0
	v_mov_b64_e32 v[62:63], 0
	v_mov_b64_e32 v[68:69], 0
	v_mov_b64_e32 v[70:71], 0
	v_mov_b64_e32 v[72:73], 0
	v_mov_b64_e32 v[74:75], 0
	v_mov_b64_e32 v[80:81], 0
	v_mov_b64_e32 v[82:83], 0
	v_mov_b64_e32 v[88:89], 0
	v_mov_b64_e32 v[90:91], 0
	v_mov_b64_e32 v[96:97], 0
	v_mov_b64_e32 v[98:99], 0
	v_mov_b64_e32 v[104:105], 0
	v_mov_b64_e32 v[106:107], 0
	v_mov_b64_e32 v[112:113], 0
	v_mov_b64_e32 v[114:115], 0
	v_mov_b64_e32 v[120:121], 0
	v_mov_b64_e32 v[122:123], 0
	v_mov_b64_e32 v[64:65], 0
	v_mov_b64_e32 v[66:67], 0
	v_mov_b64_e32 v[76:77], 0
	v_mov_b64_e32 v[78:79], 0
	v_mov_b64_e32 v[84:85], 0
	v_mov_b64_e32 v[86:87], 0
	v_mov_b64_e32 v[92:93], 0
	v_mov_b64_e32 v[94:95], 0
	v_mov_b64_e32 v[100:101], 0
	v_mov_b64_e32 v[102:103], 0
	v_mov_b64_e32 v[108:109], 0
	v_mov_b64_e32 v[110:111], 0
	v_mov_b64_e32 v[116:117], 0
	v_mov_b64_e32 v[118:119], 0
	v_mov_b64_e32 v[124:125], 0
	v_mov_b64_e32 v[126:127], 0

.LBB0_309:
	s_ashr_i32 s9, s8, 31
	s_lshl_b64 s[14:15], s[8:9], 19
	s_add_u32 s14, s24, s14
	s_addc_u32 s15, s25, s15
	s_and_b64 s[20:21], s[40:41], exec
	s_cselect_b32 s9, s15, s93
	s_cselect_b32 s20, s14, s92
	s_ashr_i32 s11, s10, 31
	s_lshl_b64 s[90:91], s[10:11], 19
	s_add_u32 s96, s26, s90
	s_addc_u32 s97, s27, s91
	s_and_b64 s[90:91], s[40:41], exec
	s_cselect_b32 s11, s97, s13
	s_cselect_b32 s45, s96, s12
	s_add_u32 s90, s12, 0x100
	s_addc_u32 s91, s13, 0
	s_add_u32 vcc_lo, s92, 0x40080
	v_mov_b64_e32 v[0:1], 0
	s_addc_u32 vcc_hi, s93, 0
	s_mov_b32 s21, -2
	v_mov_b64_e32 v[2:3], 0
	v_mov_b64_e32 v[4:5], 0
	v_mov_b64_e32 v[6:7], 0
	v_mov_b64_e32 v[16:17], 0
	v_mov_b64_e32 v[18:19], 0
	v_mov_b64_e32 v[20:21], 0
	v_mov_b64_e32 v[22:23], 0
	v_mov_b64_e32 v[32:33], 0
	v_mov_b64_e32 v[34:35], 0
	v_mov_b64_e32 v[36:37], 0
	v_mov_b64_e32 v[38:39], 0
	v_mov_b64_e32 v[48:49], 0
	v_mov_b64_e32 v[50:51], 0
	v_mov_b64_e32 v[52:53], 0
	v_mov_b64_e32 v[54:55], 0
	v_mov_b64_e32 v[8:9], 0
	v_mov_b64_e32 v[10:11], 0
	v_mov_b64_e32 v[12:13], 0
	v_mov_b64_e32 v[14:15], 0
	v_mov_b64_e32 v[24:25], 0
	v_mov_b64_e32 v[26:27], 0
	v_mov_b64_e32 v[28:29], 0
	v_mov_b64_e32 v[30:31], 0
	v_mov_b64_e32 v[40:41], 0
	v_mov_b64_e32 v[42:43], 0
	v_mov_b64_e32 v[44:45], 0
	v_mov_b64_e32 v[46:47], 0
	v_mov_b64_e32 v[56:57], 0
	v_mov_b64_e32 v[58:59], 0
	v_mov_b64_e32 v[60:61], 0
	v_mov_b64_e32 v[62:63], 0
	v_mov_b64_e32 v[64:65], 0
	v_mov_b64_e32 v[66:67], 0
	v_mov_b64_e32 v[68:69], 0
	v_mov_b64_e32 v[70:71], 0
	v_mov_b64_e32 v[80:81], 0
	v_mov_b64_e32 v[82:83], 0
	v_mov_b64_e32 v[84:85], 0
	v_mov_b64_e32 v[86:87], 0
	v_mov_b64_e32 v[96:97], 0
	v_mov_b64_e32 v[98:99], 0
	v_mov_b64_e32 v[100:101], 0
	v_mov_b64_e32 v[102:103], 0
	v_mov_b64_e32 v[112:113], 0
	v_mov_b64_e32 v[114:115], 0
	v_mov_b64_e32 v[116:117], 0
	v_mov_b64_e32 v[118:119], 0
	v_mov_b64_e32 v[72:73], 0
	v_mov_b64_e32 v[74:75], 0
	v_mov_b64_e32 v[76:77], 0
	v_mov_b64_e32 v[78:79], 0
	v_mov_b64_e32 v[88:89], 0
	v_mov_b64_e32 v[90:91], 0
	v_mov_b64_e32 v[92:93], 0
	v_mov_b64_e32 v[94:95], 0
	v_mov_b64_e32 v[104:105], 0
	v_mov_b64_e32 v[106:107], 0
	v_mov_b64_e32 v[108:109], 0
	v_mov_b64_e32 v[110:111], 0
	v_mov_b64_e32 v[120:121], 0
	v_mov_b64_e32 v[122:123], 0
	v_mov_b64_e32 v[124:125], 0
	v_mov_b64_e32 v[126:127], 0

.LBB0_398:
	s_ashr_i32 s7, s6, 31
	s_lshl_b64 s[2:3], s[6:7], 19
	s_add_u32 s2, s13, s2
	s_addc_u32 s3, s14, s3
	s_and_b64 s[4:5], s[38:39], exec
	s_cselect_b32 s7, s3, s9
	s_cselect_b32 s19, s2, s8
	s_ashr_i32 s97, s96, 31
	s_lshl_b64 s[4:5], s[96:97], 19
	s_add_u32 s4, s15, s4
	s_addc_u32 s5, s24, s5
	s_and_b64 s[10:11], s[38:39], exec
	s_cselect_b32 s20, s5, s1
	s_cselect_b32 s33, s4, s0
	s_add_u32 s90, s0, 0x100
	s_addc_u32 s91, s1, 0
	s_add_u32 s0, s8, 0x40080
	v_mov_b64_e32 v[0:1], 0
	s_addc_u32 s1, s9, 0
	s_mov_b32 s21, -2
	v_mov_b64_e32 v[2:3], 0
	v_mov_b64_e32 v[8:9], 0
	v_mov_b64_e32 v[10:11], 0
	v_mov_b64_e32 v[16:17], 0
	v_mov_b64_e32 v[18:19], 0
	v_mov_b64_e32 v[24:25], 0
	v_mov_b64_e32 v[26:27], 0
	v_mov_b64_e32 v[32:33], 0
	v_mov_b64_e32 v[34:35], 0
	v_mov_b64_e32 v[40:41], 0
	v_mov_b64_e32 v[42:43], 0
	v_mov_b64_e32 v[48:49], 0
	v_mov_b64_e32 v[50:51], 0
	v_mov_b64_e32 v[56:57], 0
	v_mov_b64_e32 v[58:59], 0
	v_mov_b64_e32 v[4:5], 0
	v_mov_b64_e32 v[6:7], 0
	v_mov_b64_e32 v[12:13], 0
	v_mov_b64_e32 v[14:15], 0
	v_mov_b64_e32 v[20:21], 0
	v_mov_b64_e32 v[22:23], 0
	v_mov_b64_e32 v[28:29], 0
	v_mov_b64_e32 v[30:31], 0
	v_mov_b64_e32 v[36:37], 0
	v_mov_b64_e32 v[38:39], 0
	v_mov_b64_e32 v[44:45], 0
	v_mov_b64_e32 v[46:47], 0
	v_mov_b64_e32 v[52:53], 0
	v_mov_b64_e32 v[54:55], 0
	v_mov_b64_e32 v[60:61], 0
	v_mov_b64_e32 v[62:63], 0
	v_mov_b64_e32 v[64:65], 0
	v_mov_b64_e32 v[66:67], 0
	v_mov_b64_e32 v[72:73], 0
	v_mov_b64_e32 v[74:75], 0
	v_mov_b64_e32 v[80:81], 0
	v_mov_b64_e32 v[82:83], 0
	v_mov_b64_e32 v[88:89], 0
	v_mov_b64_e32 v[90:91], 0
	v_mov_b64_e32 v[96:97], 0
	v_mov_b64_e32 v[98:99], 0
	v_mov_b64_e32 v[104:105], 0
	v_mov_b64_e32 v[106:107], 0
	v_mov_b64_e32 v[112:113], 0
	v_mov_b64_e32 v[114:115], 0
	v_mov_b64_e32 v[120:121], 0
	v_mov_b64_e32 v[122:123], 0
	v_mov_b64_e32 v[68:69], 0
	v_mov_b64_e32 v[70:71], 0
	v_mov_b64_e32 v[76:77], 0
	v_mov_b64_e32 v[78:79], 0
	v_mov_b64_e32 v[84:85], 0
	v_mov_b64_e32 v[86:87], 0
	v_mov_b64_e32 v[92:93], 0
	v_mov_b64_e32 v[94:95], 0
	v_mov_b64_e32 v[100:101], 0
	v_mov_b64_e32 v[102:103], 0
	v_mov_b64_e32 v[108:109], 0
	v_mov_b64_e32 v[110:111], 0
	v_mov_b64_e32 v[116:117], 0
	v_mov_b64_e32 v[118:119], 0
	v_mov_b64_e32 v[124:125], 0
	v_mov_b64_e32 v[126:127], 0

.LBB0_438:
	s_add_u32 s21, s10, 0x100
	v_mov_b64_e32 v[0:1], 0
	s_addc_u32 s92, s11, 0
	s_mov_b32 s22, -2
	v_mov_b64_e32 v[2:3], 0
	v_mov_b64_e32 v[4:5], 0
	v_mov_b64_e32 v[6:7], 0
	v_mov_b64_e32 v[16:17], 0
	v_mov_b64_e32 v[18:19], 0
	v_mov_b64_e32 v[20:21], 0
	v_mov_b64_e32 v[22:23], 0
	v_mov_b64_e32 v[32:33], 0
	v_mov_b64_e32 v[34:35], 0
	v_mov_b64_e32 v[36:37], 0
	v_mov_b64_e32 v[38:39], 0
	v_mov_b64_e32 v[48:49], 0
	v_mov_b64_e32 v[50:51], 0
	v_mov_b64_e32 v[52:53], 0
	v_mov_b64_e32 v[54:55], 0
	v_mov_b64_e32 v[8:9], 0
	v_mov_b64_e32 v[10:11], 0
	v_mov_b64_e32 v[12:13], 0
	v_mov_b64_e32 v[14:15], 0
	v_mov_b64_e32 v[24:25], 0
	v_mov_b64_e32 v[26:27], 0
	v_mov_b64_e32 v[28:29], 0
	v_mov_b64_e32 v[30:31], 0
	v_mov_b64_e32 v[40:41], 0
	v_mov_b64_e32 v[42:43], 0
	v_mov_b64_e32 v[44:45], 0
	v_mov_b64_e32 v[46:47], 0
	v_mov_b64_e32 v[56:57], 0
	v_mov_b64_e32 v[58:59], 0
	v_mov_b64_e32 v[60:61], 0
	v_mov_b64_e32 v[62:63], 0
	v_mov_b64_e32 v[64:65], 0
	v_mov_b64_e32 v[66:67], 0
	v_mov_b64_e32 v[68:69], 0
	v_mov_b64_e32 v[70:71], 0
	v_mov_b64_e32 v[80:81], 0
	v_mov_b64_e32 v[82:83], 0
	v_mov_b64_e32 v[84:85], 0
	v_mov_b64_e32 v[86:87], 0
	v_mov_b64_e32 v[96:97], 0
	v_mov_b64_e32 v[98:99], 0
	v_mov_b64_e32 v[100:101], 0
	v_mov_b64_e32 v[102:103], 0
	v_mov_b64_e32 v[112:113], 0
	v_mov_b64_e32 v[114:115], 0
	v_mov_b64_e32 v[116:117], 0
	v_mov_b64_e32 v[118:119], 0
	v_mov_b64_e32 v[72:73], 0
	v_mov_b64_e32 v[74:75], 0
	v_mov_b64_e32 v[76:77], 0
	v_mov_b64_e32 v[78:79], 0
	v_mov_b64_e32 v[88:89], 0
	v_mov_b64_e32 v[90:91], 0
	v_mov_b64_e32 v[92:93], 0
	v_mov_b64_e32 v[94:95], 0
	v_mov_b64_e32 v[104:105], 0
	v_mov_b64_e32 v[106:107], 0
	v_mov_b64_e32 v[108:109], 0
	v_mov_b64_e32 v[110:111], 0
	v_mov_b64_e32 v[120:121], 0
	v_mov_b64_e32 v[122:123], 0
	v_mov_b64_e32 v[124:125], 0
	v_mov_b64_e32 v[126:127], 0

.LBB0_473:
	s_ashr_i32 s37, s36, 31
	s_lshl_b64 s[14:15], s[36:37], 19
	s_add_u32 s44, s24, s14
	s_addc_u32 s45, s25, s15
	s_and_b64 s[14:15], s[38:39], exec
	s_cselect_b32 s20, s45, s13
	s_cselect_b32 s37, s44, s12
	s_ashr_i32 s41, s40, 31
	s_lshl_b64 s[14:15], s[40:41], 19
	s_add_u32 s46, s26, s14
	s_addc_u32 s47, s27, s15
	s_and_b64 s[14:15], s[38:39], exec
	s_cselect_b32 s41, s47, s11
	s_cselect_b32 s91, s46, s10
	s_add_u32 s92, s10, 0x100
	s_addc_u32 s93, s11, 0
	s_add_u32 s10, s12, 0x40080
	v_mov_b64_e32 v[4:5], 0
	s_addc_u32 s11, s13, 0
	s_mov_b32 s21, -2
	v_mov_b64_e32 v[6:7], 0
	v_mov_b64_e32 v[8:9], 0
	v_mov_b64_e32 v[10:11], 0
	v_mov_b64_e32 v[20:21], 0
	v_mov_b64_e32 v[22:23], 0
	v_mov_b64_e32 v[24:25], 0
	v_mov_b64_e32 v[26:27], 0
	v_mov_b64_e32 v[36:37], 0
	v_mov_b64_e32 v[38:39], 0
	v_mov_b64_e32 v[40:41], 0
	v_mov_b64_e32 v[42:43], 0
	v_mov_b64_e32 v[52:53], 0
	v_mov_b64_e32 v[54:55], 0
	v_mov_b64_e32 v[56:57], 0
	v_mov_b64_e32 v[58:59], 0
	v_mov_b64_e32 v[0:1], 0
	v_mov_b64_e32 v[2:3], 0
	v_mov_b64_e32 v[12:13], 0
	v_mov_b64_e32 v[14:15], 0
	v_mov_b64_e32 v[16:17], 0
	v_mov_b64_e32 v[18:19], 0
	v_mov_b64_e32 v[28:29], 0
	v_mov_b64_e32 v[30:31], 0
	v_mov_b64_e32 v[32:33], 0
	v_mov_b64_e32 v[34:35], 0
	v_mov_b64_e32 v[44:45], 0
	v_mov_b64_e32 v[46:47], 0
	v_mov_b64_e32 v[48:49], 0
	v_mov_b64_e32 v[50:51], 0
	v_mov_b64_e32 v[60:61], 0
	v_mov_b64_e32 v[62:63], 0
	v_mov_b64_e32 v[68:69], 0
	v_mov_b64_e32 v[70:71], 0
	v_mov_b64_e32 v[72:73], 0
	v_mov_b64_e32 v[74:75], 0
	v_mov_b64_e32 v[80:81], 0
	v_mov_b64_e32 v[82:83], 0
	v_mov_b64_e32 v[88:89], 0
	v_mov_b64_e32 v[90:91], 0
	v_mov_b64_e32 v[96:97], 0
	v_mov_b64_e32 v[98:99], 0
	v_mov_b64_e32 v[104:105], 0
	v_mov_b64_e32 v[106:107], 0
	v_mov_b64_e32 v[112:113], 0
	v_mov_b64_e32 v[114:115], 0
	v_mov_b64_e32 v[120:121], 0
	v_mov_b64_e32 v[122:123], 0
	v_mov_b64_e32 v[64:65], 0
	v_mov_b64_e32 v[66:67], 0
	v_mov_b64_e32 v[76:77], 0
	v_mov_b64_e32 v[78:79], 0
	v_mov_b64_e32 v[84:85], 0
	v_mov_b64_e32 v[86:87], 0
	v_mov_b64_e32 v[92:93], 0
	v_mov_b64_e32 v[94:95], 0
	v_mov_b64_e32 v[100:101], 0
	v_mov_b64_e32 v[102:103], 0
	v_mov_b64_e32 v[108:109], 0
	v_mov_b64_e32 v[110:111], 0
	v_mov_b64_e32 v[116:117], 0
	v_mov_b64_e32 v[118:119], 0
	v_mov_b64_e32 v[124:125], 0
	v_mov_b64_e32 v[126:127], 0
